# next DF unit Q-line prefetch issued right after the claim is folded (about 2 us of lead), wave-0 gate waits counted around it
# baseline (speedup 1.0000x reference)
.LBB0_460:
	s_waitcnt lgkmcnt(0)
	s_barrier
	s_and_b64 vcc, exec, s[4:5]
	s_cbranch_vccnz .LBB0_299
	v_mov_b32_e32 v2, v217
	s_nop 1
	v_permlane32_swap_b32_e32 v217, v2
	v_add_f32_e32 v2, v217, v2
	v_div_scale_f32 v3, s[2:3], v2, v2, 1.0
	v_rcp_f32_e32 v4, v3
	s_waitcnt vmcnt(3)
	v_min_u32_e32 v253, 0xffff, v253
	v_or_b32_e32 v95, v95, v253
	s_mov_b64 s[24:25], 0
	s_cmp_lg_u32 s63, 0
	s_cbranch_scc1 .Lqpf_end
	v_readfirstlane_b32 s21, v95
	s_lshr_b32 s22, s21, 16
	s_and_b32 s21, s21, 0xffff
	s_cmp_gt_u32 s22, 7
	s_cbranch_scc1 .Lqpf_end
	s_cmp_gt_u32 s21, 63
	s_cbranch_scc1 .Lqpf_end
	s_bfe_u32 s23, s21, 0x40001
	s_xor_b32 s23, s23, 15
	s_lshr_b32 s26, s21, 4
	s_and_b32 s26, s26, 2
	s_and_b32 s27, s21, 1
	s_or_b32 s26, s26, s27
	s_xor_b32 s26, s26, 2
	s_lshl_b32 s27, s22, 21
	s_lshl_b32 s26, s26, 19
	s_add_u32 s27, s27, s26
	s_lshl_b32 s23, s23, 15
	s_add_u32 s27, s27, s23
	s_add_u32 s27, s27, 0x4000000
	s_add_u32 s28, s78, s27
	s_addc_u32 s29, s79, 0
	v_lshlrev_b32_e32 v252, 7, v231
	global_load_dword v253, v252, s[28:29]
	v_add_u32_e32 v252, 0x2000, v252
	global_load_dword v253, v252, s[28:29]
	v_add_u32_e32 v252, 0x2000, v252
	global_load_dword v253, v252, s[28:29]
	v_add_u32_e32 v252, 0x2000, v252
	global_load_dword v253, v252, s[28:29]
	s_mov_b64 s[24:25], -1
.Lqpf_end:
	v_lshlrev_b32_e32 v110, 16, v107
	v_and_b32_e32 v111, 0xffff0000, v107
	s_lshl_b64 s[2:3], s[6:7], 22
	v_fma_f32 v5, -v3, v4, 1.0
	v_fmac_f32_e32 v4, v5, v4
	v_div_scale_f32 v5, vcc, 1.0, v2, 1.0
	v_mul_f32_e32 v6, v5, v4
	v_fma_f32 v7, -v3, v6, v5
	v_fmac_f32_e32 v6, v7, v4
	v_fma_f32 v3, -v3, v6, v5
	v_div_fmas_f32 v3, v3, v4, v6
	v_div_fixup_f32 v94, v3, v2, 1.0
	ds_read2st64_b32 v[100:101], v0 offset1:1
	ds_read2st64_b32 v[98:99], v0 offset0:2 offset1:3
	ds_read2st64_b32 v[112:113], v0 offset0:4 offset1:5
	ds_read2st64_b32 v[108:109], v0 offset0:6 offset1:7
	ds_read2st64_b32 v[124:125], v0 offset0:8 offset1:9
	ds_read2st64_b32 v[128:129], v0 offset0:10 offset1:11
	ds_read2st64_b32 v[138:139], v0 offset0:12 offset1:13
	ds_read2st64_b32 v[186:187], v0 offset0:14 offset1:15
	ds_read2st64_b32 v[140:141], v0 offset0:16 offset1:17
	ds_read2st64_b32 v[136:137], v0 offset0:18 offset1:19
	ds_read2st64_b32 v[188:189], v0 offset0:20 offset1:21
	ds_read2st64_b32 v[194:195], v0 offset0:22 offset1:23
	ds_read2st64_b32 v[200:201], v0 offset0:24 offset1:25
	ds_read2st64_b32 v[192:193], v0 offset0:26 offset1:27
	ds_read2st64_b32 v[210:211], v0 offset0:28 offset1:29
	ds_read2st64_b32 v[202:203], v0 offset0:30 offset1:31
	ds_read2st64_b32 v[216:217], v0 offset0:32 offset1:33
	ds_read2st64_b32 v[212:213], v0 offset0:34 offset1:35
	ds_read2st64_b32 v[204:205], v0 offset0:36 offset1:37
	ds_read2st64_b32 v[208:209], v0 offset0:38 offset1:39
	ds_read2st64_b32 v[190:191], v0 offset0:40 offset1:41
	ds_read2st64_b32 v[198:199], v0 offset0:42 offset1:43
	ds_read2st64_b32 v[180:181], v0 offset0:44 offset1:45
	ds_read2st64_b32 v[182:183], v0 offset0:46 offset1:47
	ds_read2st64_b32 v[114:115], v0 offset0:56 offset1:57
	ds_read2st64_b32 v[116:117], v0 offset0:58 offset1:59
	ds_read2st64_b32 v[102:103], v0 offset0:60 offset1:61
	ds_read2st64_b32 v[2:3], v0 offset0:62 offset1:63
	ds_read2st64_b32 v[142:143], v0 offset0:48 offset1:49
	ds_read2st64_b32 v[144:145], v0 offset0:50 offset1:51
	ds_read2st64_b32 v[126:127], v0 offset0:52 offset1:53
	ds_read2st64_b32 v[130:131], v0 offset0:54 offset1:55
	s_waitcnt lgkmcnt(14)
	v_pk_fma_f32 v[100:101], v[64:65], v[94:95], v[100:101] op_sel_hi:[1,0,1] neg_lo:[0,0,1] neg_hi:[0,0,1]
	v_lshlrev_b32_e32 v64, 16, v106
	s_waitcnt lgkmcnt(4)
	v_pk_fma_f32 v[86:87], v[30:31], v[94:95], v[2:3] op_sel_hi:[1,0,1] neg_lo:[0,0,1] neg_hi:[0,0,1]
	v_and_b32_e32 v65, 0xffff0000, v106
	v_mul_f32_e32 v31, 0xbfb8aa3b, v64
	v_pk_fma_f32 v[98:99], v[66:67], v[94:95], v[98:99] op_sel_hi:[1,0,1] neg_lo:[0,0,1] neg_hi:[0,0,1]
	v_exp_f32_e32 v66, v31
	v_mul_f32_e32 v31, 0xbfb8aa3b, v65
	v_exp_f32_e32 v67, v31
	v_mul_f32_e32 v106, 0xbfb8aa3b, v110
	v_add_f32_e32 v66, 1.0, v66
	v_exp_f32_e32 v118, v106
	v_add_f32_e32 v67, 1.0, v67
	v_mul_f32_e32 v106, 0xbfb8aa3b, v111
	v_rcp_f32_e32 v66, v66
	v_rcp_f32_e32 v67, v67
	v_exp_f32_e32 v119, v106
	v_mul_f32_e32 v30, v101, v101
	v_pk_fma_f32 v[30:31], v[100:101], v[100:101], v[30:31] op_sel_hi:[1,1,0]
	v_pk_mul_f32 v[106:107], v[66:67], v[64:65]
	v_add_f32_e32 v64, 1.0, v118
	v_add_f32_e32 v65, 1.0, v119
	v_rcp_f32_e32 v64, v64
	v_rcp_f32_e32 v65, v65
	v_pk_fma_f32 v[30:31], v[98:99], v[98:99], v[30:31]
	v_mul_f32_e32 v66, v99, v99
	v_pk_add_f32 v[30:31], v[66:67], v[30:31] op_sel_hi:[0,1]
	v_lshlrev_b32_e32 v66, 16, v12
	v_and_b32_e32 v67, 0xffff0000, v12
	v_mul_f32_e32 v12, 0xbfb8aa3b, v66
	v_pk_mul_f32 v[110:111], v[64:65], v[110:111]
	v_exp_f32_e32 v12, v12
	v_mul_f32_e32 v65, 0xbfb8aa3b, v67
	v_exp_f32_e32 v65, v65
	v_pk_fma_f32 v[112:113], v[68:69], v[94:95], v[112:113] op_sel_hi:[1,0,1] neg_lo:[0,0,1] neg_hi:[0,0,1]
	v_add_f32_e32 v12, 1.0, v12
	v_pk_fma_f32 v[30:31], v[112:113], v[112:113], v[30:31]
	v_mul_f32_e32 v64, v113, v113
	v_pk_add_f32 v[30:31], v[64:65], v[30:31] op_sel_hi:[0,1]
	v_rcp_f32_e32 v64, v12
	v_add_f32_e32 v12, 1.0, v65
	v_rcp_f32_e32 v65, v12
	v_lshlrev_b32_e32 v12, 16, v13
	v_and_b32_e32 v13, 0xffff0000, v13
	v_mul_f32_e32 v68, 0xbfb8aa3b, v12
	v_mul_f32_e32 v69, 0xbfb8aa3b, v13
	v_exp_f32_e32 v68, v68
	v_exp_f32_e32 v69, v69
	v_pk_mul_f32 v[118:119], v[64:65], v[66:67]
	v_pk_fma_f32 v[108:109], v[70:71], v[94:95], v[108:109] op_sel_hi:[1,0,1] neg_lo:[0,0,1] neg_hi:[0,0,1]
	v_add_f32_e32 v64, 1.0, v68
	v_add_f32_e32 v65, 1.0, v69
	v_rcp_f32_e32 v64, v64
	v_rcp_f32_e32 v65, v65
	v_pk_fma_f32 v[30:31], v[108:109], v[108:109], v[30:31]
	v_mul_f32_e32 v66, v109, v109
	v_pk_add_f32 v[30:31], v[66:67], v[30:31] op_sel_hi:[0,1]
	v_pk_mul_f32 v[122:123], v[64:65], v[12:13]
	v_lshlrev_b32_e32 v64, 16, v10
	v_pk_fma_f32 v[72:73], v[72:73], v[94:95], v[124:125] op_sel_hi:[1,0,1] neg_lo:[0,0,1] neg_hi:[0,0,1]
	v_and_b32_e32 v65, 0xffff0000, v10
	v_mul_f32_e32 v10, 0xbfb8aa3b, v64
	v_pk_fma_f32 v[12:13], v[72:73], v[72:73], v[30:31]
	v_exp_f32_e32 v10, v10
	v_mul_f32_e32 v31, 0xbfb8aa3b, v65
	v_exp_f32_e32 v31, v31
	v_mul_f32_e32 v30, v73, v73
	v_add_f32_e32 v10, 1.0, v10
	v_pk_fma_f32 v[74:75], v[74:75], v[94:95], v[128:129] op_sel_hi:[1,0,1] neg_lo:[0,0,1] neg_hi:[0,0,1]
	v_pk_add_f32 v[12:13], v[30:31], v[12:13] op_sel_hi:[0,1]
	v_rcp_f32_e32 v30, v10
	v_add_f32_e32 v10, 1.0, v31
	v_rcp_f32_e32 v31, v10
	v_lshlrev_b32_e32 v10, 16, v11
	v_and_b32_e32 v11, 0xffff0000, v11
	v_mul_f32_e32 v66, 0xbfb8aa3b, v10
	v_mul_f32_e32 v67, 0xbfb8aa3b, v11
	v_exp_f32_e32 v66, v66
	v_exp_f32_e32 v67, v67
	v_pk_mul_f32 v[124:125], v[30:31], v[64:65]
	v_pk_fma_f32 v[12:13], v[74:75], v[74:75], v[12:13]
	v_add_f32_e32 v30, 1.0, v66
	v_add_f32_e32 v31, 1.0, v67
	v_rcp_f32_e32 v30, v30
	v_rcp_f32_e32 v31, v31
	v_mul_f32_e32 v64, v75, v75
	v_pk_add_f32 v[68:69], v[64:65], v[12:13] op_sel_hi:[0,1]
	v_pk_fma_f32 v[76:77], v[76:77], v[94:95], v[138:139] op_sel_hi:[1,0,1] neg_lo:[0,0,1] neg_hi:[0,0,1]
	v_lshlrev_b32_e32 v70, 16, v134
	v_and_b32_e32 v71, 0xffff0000, v134
	v_pk_mul_f32 v[128:129], v[30:31], v[10:11]
	v_pk_fma_f32 v[30:31], v[76:77], v[76:77], v[68:69]
	v_mul_f32_e32 v69, 0xbfb8aa3b, v70
	v_mul_f32_e32 v134, 0xbfb8aa3b, v71
	v_exp_f32_e32 v69, v69
	v_exp_f32_e32 v134, v134
	v_mul_f32_e32 v68, v77, v77
	v_lshlrev_b32_e32 v138, 16, v135
	v_pk_add_f32 v[30:31], v[68:69], v[30:31] op_sel_hi:[0,1]
	v_add_f32_e32 v68, 1.0, v69
	v_add_f32_e32 v69, 1.0, v134
	v_and_b32_e32 v139, 0xffff0000, v135
	v_mul_f32_e32 v134, 0xbfb8aa3b, v138
	v_exp_f32_e32 v148, v134
	v_mul_f32_e32 v134, 0xbfb8aa3b, v139
	v_rcp_f32_e32 v68, v68
	v_rcp_f32_e32 v69, v69
	v_exp_f32_e32 v149, v134
	v_pk_fma_f32 v[136:137], v[50:51], v[94:95], v[136:137] op_sel_hi:[1,0,1] neg_lo:[0,0,1] neg_hi:[0,0,1]
	v_lshlrev_b32_e32 v50, 16, v184
	v_pk_mul_f32 v[134:135], v[68:69], v[70:71]
	v_add_f32_e32 v68, 1.0, v148
	v_add_f32_e32 v69, 1.0, v149
	v_rcp_f32_e32 v68, v68
	v_rcp_f32_e32 v69, v69
	v_and_b32_e32 v51, 0xffff0000, v184
	v_pk_fma_f32 v[140:141], v[48:49], v[94:95], v[140:141] op_sel_hi:[1,0,1] neg_lo:[0,0,1] neg_hi:[0,0,1]
	v_mul_f32_e32 v49, 0xbfb8aa3b, v50
	v_pk_mul_f32 v[138:139], v[68:69], v[138:139]
	v_mul_f32_e32 v68, 0xbfb8aa3b, v51
	v_pk_fma_f32 v[78:79], v[78:79], v[94:95], v[186:187] op_sel_hi:[1,0,1] neg_lo:[0,0,1] neg_hi:[0,0,1]
	v_exp_f32_e32 v49, v49
	v_exp_f32_e32 v68, v68
	v_pk_fma_f32 v[30:31], v[78:79], v[78:79], v[30:31]
	v_mul_f32_e32 v70, v79, v79
	v_pk_add_f32 v[30:31], v[70:71], v[30:31] op_sel_hi:[0,1]
	v_pk_fma_f32 v[30:31], v[140:141], v[140:141], v[30:31]
	v_mul_f32_e32 v48, v141, v141
	v_pk_add_f32 v[30:31], v[48:49], v[30:31] op_sel_hi:[0,1]
	v_add_f32_e32 v48, 1.0, v49
	v_add_f32_e32 v49, 1.0, v68
	v_lshlrev_b32_e32 v0, 11, v179
	v_rcp_f32_e32 v48, v48
	v_rcp_f32_e32 v49, v49
	v_lshl_add_u64 v[2:3], s[56:57], 0, v[0:1]
	v_lshlrev_b32_e32 v68, 16, v185
	v_and_b32_e32 v69, 0xffff0000, v185
	v_pk_fma_f32 v[184:185], v[54:55], v[94:95], v[194:195] op_sel_hi:[1,0,1] neg_lo:[0,0,1] neg_hi:[0,0,1]
	v_lshlrev_b32_e32 v54, 16, v146
	v_and_b32_e32 v55, 0xffff0000, v146
	v_lshl_add_u64 v[2:3], v[2:3], 0, s[2:3]
	s_lshl_b32 s80, s16, 8
	v_pk_fma_f32 v[188:189], v[52:53], v[94:95], v[188:189] op_sel_hi:[1,0,1] neg_lo:[0,0,1] neg_hi:[0,0,1]
	v_mul_f32_e32 v53, 0xbfb8aa3b, v54
	v_mul_f32_e32 v146, 0xbfb8aa3b, v55
	v_lshl_add_u64 v[2:3], v[2:3], 0, s[80:81]
	v_ashrrev_i32_e32 v179, 31, v178
	v_exp_f32_e32 v53, v53
	v_exp_f32_e32 v146, v146
	v_lshl_add_u64 v[88:89], v[178:179], 1, v[2:3]
	v_lshl_add_u32 v0, v178, 2, 0
	v_pk_mul_f32 v[178:179], v[48:49], v[50:51]
	v_pk_fma_f32 v[30:31], v[136:137], v[136:137], v[30:31]
	v_mul_f32_e32 v50, v137, v137
	v_pk_add_f32 v[30:31], v[50:51], v[30:31] op_sel_hi:[0,1]
	v_pk_fma_f32 v[30:31], v[188:189], v[188:189], v[30:31]
	v_mul_f32_e32 v52, v189, v189
	v_lshlrev_b32_e32 v148, 16, v147
	v_pk_add_f32 v[30:31], v[52:53], v[30:31] op_sel_hi:[0,1]
	v_add_f32_e32 v52, 1.0, v53
	v_add_f32_e32 v53, 1.0, v146
	v_and_b32_e32 v149, 0xffff0000, v147
	v_mul_f32_e32 v146, 0xbfb8aa3b, v148
	v_exp_f32_e32 v150, v146
	v_mul_f32_e32 v146, 0xbfb8aa3b, v149
	v_rcp_f32_e32 v52, v52
	v_rcp_f32_e32 v53, v53
	v_exp_f32_e32 v151, v146
	v_pk_fma_f32 v[30:31], v[184:185], v[184:185], v[30:31]
	v_pk_fma_f32 v[200:201], v[56:57], v[94:95], v[200:201] op_sel_hi:[1,0,1] neg_lo:[0,0,1] neg_hi:[0,0,1]
	v_pk_mul_f32 v[146:147], v[52:53], v[54:55]
	v_add_f32_e32 v52, 1.0, v150
	v_add_f32_e32 v53, 1.0, v151
	v_rcp_f32_e32 v52, v52
	v_rcp_f32_e32 v53, v53
	v_mul_f32_e32 v54, v185, v185
	v_pk_add_f32 v[30:31], v[54:55], v[30:31] op_sel_hi:[0,1]
	v_lshlrev_b32_e32 v54, 16, v132
	v_and_b32_e32 v55, 0xffff0000, v132
	v_pk_mul_f32 v[194:195], v[52:53], v[148:149]
	v_mul_f32_e32 v53, 0xbfb8aa3b, v54
	v_mul_f32_e32 v56, 0xbfb8aa3b, v55
	v_exp_f32_e32 v53, v53
	v_exp_f32_e32 v56, v56
	v_pk_fma_f32 v[30:31], v[200:201], v[200:201], v[30:31]
	v_mul_f32_e32 v52, v201, v201
	v_pk_add_f32 v[30:31], v[52:53], v[30:31] op_sel_hi:[0,1]
	v_add_f32_e32 v52, 1.0, v53
	v_add_f32_e32 v53, 1.0, v56
	v_rcp_f32_e32 v52, v52
	v_rcp_f32_e32 v53, v53
	v_pk_fma_f32 v[202:203], v[62:63], v[94:95], v[202:203] op_sel_hi:[1,0,1] neg_lo:[0,0,1] neg_hi:[0,0,1]
	v_lshlrev_b32_e32 v62, 16, v120
	v_and_b32_e32 v63, 0xffff0000, v120
	v_pk_fma_f32 v[210:211], v[60:61], v[94:95], v[210:211] op_sel_hi:[1,0,1] neg_lo:[0,0,1] neg_hi:[0,0,1]
	v_mul_f32_e32 v61, 0xbfb8aa3b, v62
	v_mul_f32_e32 v120, 0xbfb8aa3b, v63
	v_pk_fma_f32 v[192:193], v[58:59], v[94:95], v[192:193] op_sel_hi:[1,0,1] neg_lo:[0,0,1] neg_hi:[0,0,1]
	v_exp_f32_e32 v61, v61
	v_exp_f32_e32 v120, v120
	v_lshlrev_b32_e32 v56, 16, v133
	v_and_b32_e32 v57, 0xffff0000, v133
	v_pk_mul_f32 v[132:133], v[52:53], v[54:55]
	v_pk_fma_f32 v[30:31], v[192:193], v[192:193], v[30:31]
	v_mul_f32_e32 v54, v193, v193
	v_pk_add_f32 v[30:31], v[54:55], v[30:31] op_sel_hi:[0,1]
	v_pk_fma_f32 v[30:31], v[210:211], v[210:211], v[30:31]
	v_mul_f32_e32 v60, v211, v211
	v_lshlrev_b32_e32 v148, 16, v121
	v_pk_add_f32 v[30:31], v[60:61], v[30:31] op_sel_hi:[0,1]
	v_add_f32_e32 v60, 1.0, v61
	v_add_f32_e32 v61, 1.0, v120
	v_and_b32_e32 v149, 0xffff0000, v121
	v_mul_f32_e32 v120, 0xbfb8aa3b, v148
	v_exp_f32_e32 v150, v120
	v_mul_f32_e32 v120, 0xbfb8aa3b, v149
	v_rcp_f32_e32 v60, v60
	v_rcp_f32_e32 v61, v61
	v_exp_f32_e32 v151, v120
	v_pk_fma_f32 v[212:213], v[34:35], v[94:95], v[212:213] op_sel_hi:[1,0,1] neg_lo:[0,0,1] neg_hi:[0,0,1]
	v_lshlrev_b32_e32 v34, 16, v104
	v_pk_mul_f32 v[120:121], v[60:61], v[62:63]
	v_add_f32_e32 v60, 1.0, v150
	v_add_f32_e32 v61, 1.0, v151
	v_rcp_f32_e32 v60, v60
	v_rcp_f32_e32 v61, v61
	v_and_b32_e32 v35, 0xffff0000, v104
	v_pk_fma_f32 v[216:217], v[32:33], v[94:95], v[216:217] op_sel_hi:[1,0,1] neg_lo:[0,0,1] neg_hi:[0,0,1]
	v_mul_f32_e32 v33, 0xbfb8aa3b, v34
	v_pk_mul_f32 v[214:215], v[60:61], v[148:149]
	v_mul_f32_e32 v60, 0xbfb8aa3b, v35
	v_exp_f32_e32 v33, v33
	v_exp_f32_e32 v60, v60
	v_pk_fma_f32 v[30:31], v[202:203], v[202:203], v[30:31]
	v_mul_f32_e32 v62, v203, v203
	v_pk_add_f32 v[30:31], v[62:63], v[30:31] op_sel_hi:[0,1]
	v_pk_fma_f32 v[30:31], v[216:217], v[216:217], v[30:31]
	v_mul_f32_e32 v32, v217, v217
	v_pk_add_f32 v[30:31], v[32:33], v[30:31] op_sel_hi:[0,1]
	v_add_f32_e32 v32, 1.0, v33
	v_add_f32_e32 v33, 1.0, v60
	v_rcp_f32_e32 v32, v32
	v_rcp_f32_e32 v33, v33
	v_pk_fma_f32 v[208:209], v[38:39], v[94:95], v[208:209] op_sel_hi:[1,0,1] neg_lo:[0,0,1] neg_hi:[0,0,1]
	v_lshlrev_b32_e32 v38, 16, v96
	v_and_b32_e32 v39, 0xffff0000, v96
	v_pk_fma_f32 v[204:205], v[36:37], v[94:95], v[204:205] op_sel_hi:[1,0,1] neg_lo:[0,0,1] neg_hi:[0,0,1]
	v_mul_f32_e32 v37, 0xbfb8aa3b, v38
	v_mul_f32_e32 v96, 0xbfb8aa3b, v39
	v_exp_f32_e32 v37, v37
	v_exp_f32_e32 v96, v96
	v_lshlrev_b32_e32 v60, 16, v105
	v_and_b32_e32 v61, 0xffff0000, v105
	v_pk_mul_f32 v[104:105], v[32:33], v[34:35]
	v_pk_fma_f32 v[30:31], v[212:213], v[212:213], v[30:31]
	v_mul_f32_e32 v34, v213, v213
	v_pk_add_f32 v[34:35], v[34:35], v[30:31] op_sel_hi:[0,1]
	v_pk_fma_f32 v[34:35], v[204:205], v[204:205], v[34:35]
	v_mul_f32_e32 v36, v205, v205
	v_lshlrev_b32_e32 v148, 16, v97
	v_pk_add_f32 v[34:35], v[36:37], v[34:35] op_sel_hi:[0,1]
	v_add_f32_e32 v36, 1.0, v37
	v_add_f32_e32 v37, 1.0, v96
	v_and_b32_e32 v149, 0xffff0000, v97
	v_mul_f32_e32 v96, 0xbfb8aa3b, v148
	v_exp_f32_e32 v150, v96
	v_mul_f32_e32 v96, 0xbfb8aa3b, v149
	v_rcp_f32_e32 v36, v36
	v_rcp_f32_e32 v37, v37
	v_exp_f32_e32 v151, v96
	v_pk_fma_f32 v[34:35], v[208:209], v[208:209], v[34:35]
	v_pk_fma_f32 v[190:191], v[40:41], v[94:95], v[190:191] op_sel_hi:[1,0,1] neg_lo:[0,0,1] neg_hi:[0,0,1]
	v_pk_mul_f32 v[96:97], v[36:37], v[38:39]
	v_add_f32_e32 v36, 1.0, v150
	v_add_f32_e32 v37, 1.0, v151
	v_rcp_f32_e32 v36, v36
	v_rcp_f32_e32 v37, v37
	v_mul_f32_e32 v38, v209, v209
	v_pk_add_f32 v[34:35], v[38:39], v[34:35] op_sel_hi:[0,1]
	v_lshlrev_b32_e32 v38, 16, v92
	v_and_b32_e32 v39, 0xffff0000, v92
	v_pk_mul_f32 v[220:221], v[36:37], v[148:149]
	v_mul_f32_e32 v37, 0xbfb8aa3b, v38
	v_mul_f32_e32 v40, 0xbfb8aa3b, v39
	v_exp_f32_e32 v37, v37
	v_exp_f32_e32 v40, v40
	v_pk_fma_f32 v[34:35], v[190:191], v[190:191], v[34:35]
	v_mul_f32_e32 v36, v191, v191
	v_pk_add_f32 v[34:35], v[36:37], v[34:35] op_sel_hi:[0,1]
	v_add_f32_e32 v36, 1.0, v37
	v_add_f32_e32 v37, 1.0, v40
	v_lshlrev_b32_e32 v40, 16, v93
	v_and_b32_e32 v41, 0xffff0000, v93
	v_pk_fma_f32 v[198:199], v[42:43], v[94:95], v[198:199] op_sel_hi:[1,0,1] neg_lo:[0,0,1] neg_hi:[0,0,1]
	v_rcp_f32_e32 v36, v36
	v_rcp_f32_e32 v37, v37
	v_mul_f32_e32 v42, 0xbfb8aa3b, v40
	v_mul_f32_e32 v43, 0xbfb8aa3b, v41
	v_exp_f32_e32 v42, v42
	v_exp_f32_e32 v43, v43
	v_lshlrev_b32_e32 v148, 16, v90
	v_and_b32_e32 v149, 0xffff0000, v90
	v_pk_fma_f32 v[180:181], v[44:45], v[94:95], v[180:181] op_sel_hi:[1,0,1] neg_lo:[0,0,1] neg_hi:[0,0,1]
	v_mul_f32_e32 v45, 0xbfb8aa3b, v148
	v_mul_f32_e32 v90, 0xbfb8aa3b, v149
	v_exp_f32_e32 v45, v45
	v_exp_f32_e32 v90, v90
	v_pk_mul_f32 v[92:93], v[36:37], v[38:39]
	v_pk_fma_f32 v[34:35], v[198:199], v[198:199], v[34:35]
	v_mul_f32_e32 v38, v199, v199
	v_add_f32_e32 v36, 1.0, v42
	v_add_f32_e32 v37, 1.0, v43
	v_pk_add_f32 v[42:43], v[38:39], v[34:35] op_sel_hi:[0,1]
	v_pk_fma_f32 v[42:43], v[180:181], v[180:181], v[42:43]
	v_mul_f32_e32 v44, v181, v181
	v_lshlrev_b32_e32 v150, 16, v91
	v_pk_add_f32 v[42:43], v[44:45], v[42:43] op_sel_hi:[0,1]
	v_add_f32_e32 v44, 1.0, v45
	v_add_f32_e32 v45, 1.0, v90
	v_and_b32_e32 v151, 0xffff0000, v91
	v_mul_f32_e32 v90, 0xbfb8aa3b, v150
	v_pk_fma_f32 v[46:47], v[46:47], v[94:95], v[182:183] op_sel_hi:[1,0,1] neg_lo:[0,0,1] neg_hi:[0,0,1]
	v_exp_f32_e32 v182, v90
	v_mul_f32_e32 v90, 0xbfb8aa3b, v151
	v_rcp_f32_e32 v44, v44
	v_rcp_f32_e32 v45, v45
	v_exp_f32_e32 v183, v90
	v_pk_fma_f32 v[42:43], v[46:47], v[46:47], v[42:43]
	s_waitcnt lgkmcnt(3)
	v_pk_fma_f32 v[142:143], v[16:17], v[94:95], v[142:143] op_sel_hi:[1,0,1] neg_lo:[0,0,1] neg_hi:[0,0,1]
	v_pk_mul_f32 v[90:91], v[44:45], v[148:149]
	v_add_f32_e32 v44, 1.0, v182
	v_add_f32_e32 v45, 1.0, v183
	v_rcp_f32_e32 v44, v44
	v_rcp_f32_e32 v45, v45
	v_mul_f32_e32 v148, v47, v47
	v_pk_add_f32 v[42:43], v[148:149], v[42:43] op_sel_hi:[0,1]
	v_pk_fma_f32 v[16:17], v[142:143], v[142:143], v[42:43]
	v_pk_mul_f32 v[182:183], v[44:45], v[150:151]
	v_lshlrev_b32_e32 v44, 16, v14
	v_and_b32_e32 v45, 0xffff0000, v14
	v_mul_f32_e32 v14, 0xbfb8aa3b, v44
	v_exp_f32_e32 v14, v14
	v_mul_f32_e32 v43, 0xbfb8aa3b, v45
	v_exp_f32_e32 v43, v43
	v_mul_f32_e32 v42, v143, v143
	v_add_f32_e32 v14, 1.0, v14
	s_waitcnt lgkmcnt(2)
	v_pk_fma_f32 v[18:19], v[18:19], v[94:95], v[144:145] op_sel_hi:[1,0,1] neg_lo:[0,0,1] neg_hi:[0,0,1]
	v_pk_add_f32 v[16:17], v[42:43], v[16:17] op_sel_hi:[0,1]
	v_rcp_f32_e32 v42, v14
	v_add_f32_e32 v14, 1.0, v43
	v_rcp_f32_e32 v43, v14
	v_lshlrev_b32_e32 v14, 16, v15
	v_and_b32_e32 v15, 0xffff0000, v15
	v_mul_f32_e32 v144, 0xbfb8aa3b, v14
	v_exp_f32_e32 v148, v144
	v_mul_f32_e32 v144, 0xbfb8aa3b, v15
	v_exp_f32_e32 v149, v144
	v_pk_mul_f32 v[144:145], v[42:43], v[44:45]
	v_pk_fma_f32 v[16:17], v[18:19], v[18:19], v[16:17]
	v_mul_f32_e32 v44, v19, v19
	v_add_f32_e32 v42, 1.0, v148
	v_add_f32_e32 v43, 1.0, v149
	v_pk_add_f32 v[148:149], v[44:45], v[16:17] op_sel_hi:[0,1]
	s_waitcnt lgkmcnt(1)
	v_pk_fma_f32 v[20:21], v[20:21], v[94:95], v[126:127] op_sel_hi:[1,0,1] neg_lo:[0,0,1] neg_hi:[0,0,1]
	s_waitcnt lgkmcnt(0)
	v_pk_fma_f32 v[22:23], v[22:23], v[94:95], v[130:131] op_sel_hi:[1,0,1] neg_lo:[0,0,1] neg_hi:[0,0,1]
	v_pk_fma_f32 v[126:127], v[20:21], v[20:21], v[148:149]
	s_and_b64 vcc, exec, s[24:25]
	s_cbranch_vccz .Lqpf_w1a
	s_waitcnt vmcnt(6)
	s_branch .Lqpf_w1b
.Lqpf_w1a:
	s_waitcnt vmcnt(2)
.Lqpf_w1b:
	v_lshlrev_b32_e32 v148, 16, v84
	v_and_b32_e32 v149, 0xffff0000, v84
	v_mul_f32_e32 v84, 0xbfb8aa3b, v148
	v_exp_f32_e32 v84, v84
	v_mul_f32_e32 v131, 0xbfb8aa3b, v149
	v_exp_f32_e32 v131, v131
	v_mul_f32_e32 v130, v21, v21
	v_add_f32_e32 v84, 1.0, v84
	v_lshlrev_b32_e32 v150, 16, v85
	v_pk_add_f32 v[126:127], v[130:131], v[126:127] op_sel_hi:[0,1]
	v_rcp_f32_e32 v130, v84
	v_add_f32_e32 v84, 1.0, v131
	v_rcp_f32_e32 v131, v84
	v_and_b32_e32 v151, 0xffff0000, v85
	v_mul_f32_e32 v84, 0xbfb8aa3b, v150
	v_exp_f32_e32 v233, v84
	v_mul_f32_e32 v84, 0xbfb8aa3b, v151
	v_exp_f32_e32 v234, v84
	v_pk_mul_f32 v[84:85], v[130:131], v[148:149]
	v_add_f32_e32 v130, 1.0, v233
	v_rcp_f32_e32 v130, v130
	v_add_f32_e32 v131, 1.0, v234
	v_rcp_f32_e32 v131, v131
	v_pk_fma_f32 v[26:27], v[26:27], v[94:95], v[116:117] op_sel_hi:[1,0,1] neg_lo:[0,0,1] neg_hi:[0,0,1]
	s_and_b64 vcc, exec, s[24:25]
	s_cbranch_vccz .Lqpf_w2a
	s_waitcnt vmcnt(5)
	s_branch .Lqpf_w2b
.Lqpf_w2a:
	s_waitcnt vmcnt(1)
.Lqpf_w2b:
	v_lshlrev_b32_e32 v116, 16, v82
	v_pk_fma_f32 v[126:127], v[22:23], v[22:23], v[126:127]
	v_mul_f32_e32 v148, v23, v23
	v_and_b32_e32 v117, 0xffff0000, v82
	v_mul_f32_e32 v82, 0xbfb8aa3b, v116
	v_pk_add_f32 v[148:149], v[148:149], v[126:127] op_sel_hi:[0,1]
	v_pk_mul_f32 v[126:127], v[130:131], v[150:151]
	v_exp_f32_e32 v82, v82
	v_mul_f32_e32 v130, 0xbfb8aa3b, v117
	v_exp_f32_e32 v130, v130
	v_pk_fma_f32 v[24:25], v[24:25], v[94:95], v[114:115] op_sel_hi:[1,0,1] neg_lo:[0,0,1] neg_hi:[0,0,1]
	v_add_f32_e32 v82, 1.0, v82
	v_rcp_f32_e32 v114, v82
	v_add_f32_e32 v82, 1.0, v130
	v_rcp_f32_e32 v115, v82
	v_pk_fma_f32 v[130:131], v[24:25], v[24:25], v[148:149]
	v_mul_f32_e32 v82, v25, v25
	v_pk_add_f32 v[130:131], v[82:83], v[130:131] op_sel_hi:[0,1]
	v_lshlrev_b32_e32 v82, 16, v83
	v_pk_mul_f32 v[234:235], v[114:115], v[116:117]
	v_mul_f32_e32 v116, 0xbfb8aa3b, v82
	v_exp_f32_e32 v117, v116
	v_pk_fma_f32 v[114:115], v[26:27], v[26:27], v[130:131]
	v_mul_f32_e32 v116, v27, v27
	v_pk_fma_f32 v[28:29], v[28:29], v[94:95], v[102:103] op_sel_hi:[1,0,1] neg_lo:[0,0,1] neg_hi:[0,0,1]
	v_pk_add_f32 v[114:115], v[116:117], v[114:115] op_sel_hi:[0,1]
	v_pk_fma_f32 v[102:103], v[28:29], v[28:29], v[114:115]
	v_mul_f32_e32 v94, v29, v29
	v_pk_add_f32 v[102:103], v[94:95], v[102:103] op_sel_hi:[0,1]
	v_pk_fma_f32 v[102:103], v[86:87], v[86:87], v[102:103]
	v_mul_f32_e32 v94, v87, v87
	v_pk_add_f32 v[102:103], v[94:95], v[102:103] op_sel_hi:[0,1]
	v_mov_b32_e32 v94, v102
	s_nop 1
	v_permlane32_swap_b32_e32 v102, v94
	v_add_f32_e32 v94, v102, v94
	v_mov_b32_e32 v102, 0x358637bd
	v_fmamk_f32 v94, v94, 0x3c000000, v102
	s_mov_b32 s2, 0xf800000
	v_mul_f32_e32 v102, 0x4f800000, v94
	v_cmp_gt_f32_e32 vcc, s2, v94
	v_add_f32_e32 v116, 1.0, v117
	v_mul_f32_e32 v70, 0xbfb8aa3b, v68
	v_cndmask_b32_e32 v94, v94, v102, vcc
	v_sqrt_f32_e32 v114, v94
	v_rcp_f32_e32 v102, v116
	v_mul_f32_e32 v71, 0xbfb8aa3b, v69
	v_mul_f32_e32 v58, 0xbfb8aa3b, v56
	v_add_u32_e32 v115, -1, v114
	v_fma_f32 v116, -v115, v114, v94
	v_cmp_ge_f32_e64 s[4:5], 0, v116
	v_add_u32_e32 v116, 1, v114
	v_mul_f32_e32 v59, 0xbfb8aa3b, v57
	v_cndmask_b32_e64 v115, v114, v115, s[4:5]
	v_fma_f32 v114, -v116, v114, v94
	v_mul_f32_e32 v62, 0xbfb8aa3b, v60
	v_mul_f32_e32 v63, 0xbfb8aa3b, v61
	v_cmp_lt_f32_e64 s[4:5], 0, v114
	v_exp_f32_e32 v70, v70
	v_exp_f32_e32 v71, v71
	v_exp_f32_e32 v58, v58
	v_exp_f32_e32 v59, v59
	v_exp_f32_e32 v62, v62
	v_exp_f32_e32 v63, v63
	v_and_b32_e32 v83, 0xffff0000, v83
	v_cndmask_b32_e64 v114, v115, v116, s[4:5]
	v_mul_f32_e32 v117, 0xbfb8aa3b, v83
	v_mul_f32_e32 v115, 0x37800000, v114
	v_exp_f32_e32 v117, v117
	v_cndmask_b32_e32 v114, v114, v115, vcc
	v_cmp_class_f32_e32 vcc, v94, v232
	s_mov_b32 s4, 0x3f4ccccd
	v_add_f32_e32 v48, 1.0, v70
	v_cndmask_b32_e32 v94, v114, v94, vcc
	v_add_f32_e32 v49, 1.0, v71
	v_add_f32_e32 v52, 1.0, v58
	v_add_f32_e32 v53, 1.0, v59
	v_add_f32_e32 v32, 1.0, v62
	v_add_f32_e32 v33, 1.0, v63
	v_div_scale_f32 v130, s[2:3], v94, v94, s4
	v_rcp_f32_e32 v48, v48
	v_rcp_f32_e32 v49, v49
	v_rcp_f32_e32 v52, v52
	v_rcp_f32_e32 v53, v53
	v_rcp_f32_e32 v32, v32
	v_rcp_f32_e32 v33, v33
	v_rcp_f32_e32 v36, v36
	v_rcp_f32_e32 v37, v37
	v_rcp_f32_e32 v42, v42
	v_rcp_f32_e32 v43, v43
	v_rcp_f32_e32 v131, v130
	v_add_f32_e32 v103, 1.0, v117
	v_rcp_f32_e32 v103, v103
	v_add_u32_e32 v0, 0x24800, v0
	ds_read_b128 v[6:9], v0
	ds_read_b128 v[2:5], v0 offset:32
	ds_read_b128 v[64:67], v0 offset:64
	ds_read_b128 v[10:13], v0 offset:96
	v_pk_mul_f32 v[186:187], v[48:49], v[68:69]
	ds_read_b128 v[68:71], v0 offset:128
	ds_read_b128 v[48:51], v0 offset:160
	v_pk_mul_f32 v[206:207], v[52:53], v[56:57]
	ds_read_b128 v[56:59], v0 offset:192
	ds_read_b128 v[52:55], v0 offset:224
	v_pk_mul_f32 v[218:219], v[32:33], v[60:61]
	ds_read_b128 v[60:63], v0 offset:256
	ds_read_b128 v[30:33], v0 offset:288
	v_pk_mul_f32 v[222:223], v[36:37], v[40:41]
	ds_read_b128 v[38:41], v0 offset:320
	ds_read_b128 v[34:37], v0 offset:352
	v_pk_mul_f32 v[224:225], v[42:43], v[14:15]
	ds_read_b128 v[42:45], v0 offset:384
	ds_read_b128 v[14:17], v0 offset:416
	ds_read_b128 v[114:117], v0 offset:448
	ds_read_b128 v[148:151], v0 offset:480
	v_fma_f32 v0, -v130, v131, 1.0
	v_fmac_f32_e32 v131, v0, v131
	v_div_scale_f32 v0, vcc, s4, v94, s4
	v_pk_mul_f32 v[82:83], v[102:103], v[82:83]
	v_mul_f32_e32 v102, v0, v131
	v_fma_f32 v103, -v130, v102, v0
	v_fmac_f32_e32 v102, v103, v131
	v_fma_f32 v0, -v130, v102, v0
	v_div_fmas_f32 v0, v0, v131, v102
	v_div_fixup_f32 v0, v0, v94, s4
	v_pk_mul_f32 v[100:101], v[100:101], v[0:1] op_sel_hi:[1,0]
	v_pk_mul_f32 v[98:99], v[98:99], v[0:1] op_sel_hi:[1,0]
	s_waitcnt lgkmcnt(14)
	v_pk_mul_f32 v[6:7], v[6:7], v[100:101]
	v_pk_mul_f32 v[8:9], v[8:9], v[98:99]
	v_pk_mul_f32 v[6:7], v[106:107], v[6:7]
	v_pk_mul_f32 v[8:9], v[110:111], v[8:9]
	v_cvt_pk_bf16_f32 v6, v6, v7
	v_cvt_pk_bf16_f32 v7, v8, v9
	global_store_dwordx2 v[88:89], v[6:7], off offset:1024
	v_pk_mul_f32 v[6:7], v[112:113], v[0:1] op_sel_hi:[1,0]
	s_nop 0
	v_pk_mul_f32 v[2:3], v[2:3], v[6:7]
	v_pk_mul_f32 v[6:7], v[108:109], v[0:1] op_sel_hi:[1,0]
	v_pk_mul_f32 v[2:3], v[118:119], v[2:3]
	v_pk_mul_f32 v[4:5], v[4:5], v[6:7]
	v_cvt_pk_bf16_f32 v2, v2, v3
	v_pk_mul_f32 v[4:5], v[122:123], v[4:5]
	s_and_b64 vcc, exec, s[24:25]
	s_cbranch_vccz .Lqpf_w3a
	s_waitcnt vmcnt(5)
	s_branch .Lqpf_w3b
